# weight-conversion jobs moved from the down/out GEMM phases into the idle last-round slots of the gate/up GEMM phases
# baseline (speedup 1.0000x reference)
; __device__ void run_phase(const KP& p_, int ph) {
;     ...
;     else if (q == 9) gemm_phase<1, NGU, DM>(p, l, hb, Wl + W_GUB);
.LBB0_293:
	s_mov_b64 s[2:3], 0
	s_mov_b64 s[88:89], -1
	v_readlane_b32 s98, v255, 53
	v_readlane_b32 s99, v255, 54
	s_nop 3
	s_and_b64 s[98:99], s[98:99], exec
	s_cselect_b32 s33, 0x1d80, 0
	s_cselect_b32 s95, 0x1540, 0
	s_cselect_b32 s67, 0x58, 16
	s_and_b64 vcc, exec, s[0:1]
	s_cbranch_vccz .LBB0_308

; __device__ void run_phase(const KP& p_, int ph) {
;     ...
;     else if (q == 7) { gemm_phase<2, DM, DM>(p, l, mix, Wl + W_OUT); if (l == 0) { plo = 5440; phi = 6140; } }
.LBB0_307:
	v_readlane_b32 s0, v255, 53
	v_readlane_b32 s1, v255, 54
	s_and_b64 s[0:1], s[0:1], exec
	s_mov_b32 s33, 0
	s_mov_b32 s95, 0
	s_mov_b64 s[2:3], 0
	s_mov_b64 s[88:89], -1
	s_mov_b32 s67, 16

; __device__ void run_phase(const KP& p_, int ph) {
;     ...
;     else { gemm_phase<2, DM, DFF>(p, l, U, Wl + W_DB); if (l == 0) { plo = 6140; phi = 7552; } }
.LBB0_1137:
	v_readlane_b32 s0, v255, 53
	v_readlane_b32 s1, v255, 54
	s_and_b64 s[0:1], s[0:1], exec
	s_mov_b32 s33, 0
	s_mov_b32 s95, 0
	s_mov_b64 s[44:45], 0
	s_mov_b64 s[88:89], -1
	s_mov_b32 s67, 16

; __device__ void run_phase(const KP& p_, int ph) {
;     ...
;     if (q == 0) { gemm_phase<1, NGU, DM>(p, l, hb, Wl + W_GUA); if (l == 0) { plo = 1408; phi = 2112; pfirst = (132 * 22) % p.nblk; } }
.LBB0_1151:
	v_readlane_b32 s0, v255, 53
	v_readlane_b32 s1, v255, 54
	s_andn2_b64 vcc, exec, s[0:1]
	s_cbranch_vccnz .LBB0_1153
	v_readlane_b32 s0, v255, 43
	s_abs_i32 s0, s0
	v_readlane_b32 s1, v255, 44
	v_cvt_f32_u32_e32 v0, s0
	s_sub_i32 s1, 0, s0
	s_movk_i32 s33, 0x1540
	s_movk_i32 s95, 0x580
	v_rcp_iflag_f32_e32 v0, v0
	s_nop 0
	v_mul_f32_e32 v0, 0x4f7ffffe, v0
	v_cvt_u32_f32_e32 v0, v0
	s_nop 0
	v_readfirstlane_b32 s2, v0
	s_mul_i32 s1, s1, s2
	s_mul_hi_u32 s1, s2, s1
	s_add_i32 s2, s2, s1
	s_mul_hi_u32 s1, s2, 0xb58
	s_mul_i32 s1, s1, s0
	s_sub_i32 s1, 0xb58, s1
	s_sub_i32 s2, s1, s0
	s_cmp_ge_u32 s1, s0
	s_cselect_b32 s1, s2, s1
	s_sub_i32 s2, s1, s0
	s_cmp_ge_u32 s1, s0
	s_cselect_b32 s67, s2, s1
	s_mov_b64 s[88:89], -1
	s_branch .LBB0_27
.LBB0_1153:
	s_movk_i32 s67, 0x58
	s_movk_i32 s95, 0x1d80
	s_movk_i32 s33, 0x2a80
	s_mov_b64 s[88:89], -1
	s_branch .LBB0_27

; __device__ void run_phase(const KP& p_, int ph) {
;     ...
;     else if (q == 1) { gemm_phase<2, DM, DFF>(p, l, U, Wl + W_DA); if (l == 0) { plo = 2112; phi = 5440; } else { plo = 7552; phi = 10880; } }
.LBB0_1167:
	v_readlane_b32 s0, v255, 53
	v_readlane_b32 s1, v255, 54
	s_and_b64 s[0:1], s[0:1], exec
	s_movk_i32 s0, 0x2a80
	s_mov_b32 s33, 0
	s_movk_i32 s0, 0x840
	s_mov_b32 s95, 0
	s_mov_b64 s[0:1], 0
	v_writelane_b32 v255, s0, 62
	s_mov_b64 s[88:89], -1
	s_mov_b32 s67, 16
	v_writelane_b32 v255, s1, 63
	s_mov_b64 s[44:45], 0
	s_branch .LBB0_1125
